# prologue grid sync through the XCD-hierarchical barrier instead of cooperative-groups grid.sync
# speedup vs baseline: 1.0125x; 1.0125x over previous
.LBB0_36:
	s_or_b64 exec, exec, s[12:13]
	v_lshrrev_b32_e32 v1, 20, v0
	v_lshrrev_b32_e32 v0, 10, v0
	v_or_b32_e32 v0, v0, v1
	s_movk_i32 s3, 0x3ff
	v_and_or_b32 v0, v0, s3, v224
	v_cmp_eq_u32_e32 vcc, 0, v0
	s_barrier
	s_and_saveexec_b64 s[4:5], vcc
	s_xor_b64 s[4:5], exec, s[4:5]
	v_writelane_b32 v253, s82, 59
	s_nop 1
	v_writelane_b32 v253, s83, 60
	s_branch .LBB0_46
.LBB0_46:
	s_or_b64 exec, exec, s[4:5]
	s_load_dwordx8 s[52:59], s[0:1], 0x70
	s_load_dwordx2 s[14:15], s[0:1], 0x88
	s_mul_i32 s7, s79, s78
	s_mov_b32 s68, 0
	s_load_dwordx2 s[22:23], s[0:1], 0x20
	s_load_dwordx8 s[60:67], s[0:1], 0x30
	s_waitcnt lgkmcnt(0)
	s_add_u32 s16, s14, 0x1000000
	s_addc_u32 s17, s15, 0
	s_cmp_lt_i32 s82, s78
	s_cselect_b64 s[4:5], -1, 0
	s_cmpk_lt_i32 s82, 0xc00
	s_cselect_b64 s[8:9], -1, 0
	s_ashr_i32 s81, s82, 31
	s_and_b64 s[8:9], s[8:9], s[4:5]
	s_lshr_b32 s3, s81, 29
	v_writelane_b32 v252, s8, 2
	s_add_i32 s3, s82, s3
	s_ashr_i32 s79, s78, 31
	v_writelane_b32 v252, s9, 3
	s_ashr_i32 s8, s3, 3
	s_and_b32 s3, s3, -8
	s_sub_i32 s9, s82, s3
	s_add_u32 s12, s14, 0x9080000
	s_addc_u32 s13, s15, 0
	v_writelane_b32 v252, s12, 4
	s_add_u32 s3, s56, 0x10300000
	v_mov_b32_e32 v226, 0x358637bd
	v_writelane_b32 v252, s13, 5
	v_writelane_b32 v252, s3, 6
	s_addc_u32 s3, s57, 0
	v_writelane_b32 v252, s3, 7
	s_add_u32 s3, s56, 0x10740000
	v_writelane_b32 v252, s3, 8
	s_addc_u32 s3, s57, 0
	v_writelane_b32 v252, s3, 9
	s_add_u32 s3, s56, 0x10100000
	v_writelane_b32 v252, s3, 10
	s_addc_u32 s3, s57, 0
	v_writelane_b32 v252, s3, 11
	s_add_u32 s3, s56, 0x10700000
	v_writelane_b32 v252, s3, 12
	s_addc_u32 s3, s57, 0
	v_writelane_b32 v252, s3, 13
	s_add_u32 s3, s14, 0x2f584400
	v_writelane_b32 v252, s3, 14
	s_addc_u32 s3, s15, 0
	s_add_u32 s84, s14, 0x2f544000
	s_addc_u32 s85, s15, 0
	s_add_u32 s92, s14, 0x2f7c4e00
	s_addc_u32 s93, s15, 0
	s_add_u32 s94, s14, 0x2f7c5000
	s_addc_u32 s95, s15, 0
	s_add_u32 s96, s14, 0x2f7c5100
	s_addc_u32 s97, s15, 0
	s_add_u32 s88, s14, 0x2f7c5200
	s_addc_u32 s89, s15, 0
	s_add_u32 s40, s14, 0x2f7c5300
	s_addc_u32 s41, s15, 0
	s_add_u32 s12, s14, 0x2f7c5400
	v_writelane_b32 v252, s3, 15
	s_addc_u32 s13, s15, 0
	v_writelane_b32 v252, s12, 16
	v_mov_b32_e32 v227, 0x3727c5ac
	v_mov_b64_e32 v[190:191], 0xc00
	v_writelane_b32 v252, s13, 17
	s_add_u32 s12, s14, 0x2f7c5500
	s_addc_u32 s13, s15, 0
	v_writelane_b32 v252, s12, 18
	v_mov_b64_e32 v[192:193], 0xbff
	v_mov_b32_e32 v228, 0xfff84000
	v_writelane_b32 v252, s13, 19
	s_add_u32 s12, s14, 0x2f7c5600
	s_addc_u32 s13, s15, 0
	v_writelane_b32 v252, s12, 20
	v_mov_b32_e32 v230, 0x80
	v_mov_b32_e32 v231, 0x90
	v_writelane_b32 v252, s13, 21
	s_add_u32 s12, s14, 0x2f7c5700
	s_addc_u32 s13, s15, 0
	v_writelane_b32 v252, s12, 22
	v_mov_b32_e32 v232, 0xa0
	v_mov_b32_e32 v233, 0xb0
	v_writelane_b32 v252, s13, 23
	s_add_u32 s12, s14, 0x2f7c5800
	s_addc_u32 s13, s15, 0
	v_writelane_b32 v252, s12, 24
	v_mov_b64_e32 v[194:195], 0x400
	v_mov_b64_e32 v[196:197], 0x3ff
	v_writelane_b32 v252, s13, 25
	s_add_u32 s12, s14, 0x2f7c5900
	s_addc_u32 s13, s15, 0
	v_writelane_b32 v252, s12, 26
	s_movk_i32 s31, 0x90
	s_movk_i32 s36, 0x1800
	v_writelane_b32 v252, s13, 27
	s_add_u32 s12, s14, 0x2f7c5a00
	s_addc_u32 s13, s15, 0
	v_writelane_b32 v252, s12, 28
	s_mov_b32 s24, 0x9080000
	s_mov_b32 s30, 0x21200000
	v_writelane_b32 v252, s13, 29
	s_add_u32 s12, s14, 0x2f7c5b00
	s_addc_u32 s13, s15, 0
	v_writelane_b32 v252, s12, 30
	s_mov_b32 s86, 0x800000
	s_mov_b32 s50, 0
	v_writelane_b32 v252, s13, 31
	s_add_u32 s12, s14, 0x2f7c5c00
	s_addc_u32 s13, s15, 0
	v_writelane_b32 v252, s12, 32
	s_mov_b64 s[38:39], -1
	s_mov_b64 s[48:49], 0x80
	v_writelane_b32 v252, s13, 33
	s_add_u32 s12, s14, 0x2f7c5d00
	s_addc_u32 s13, s15, 0
	v_writelane_b32 v252, s12, 34
	s_mov_b64 s[26:27], 0x60000
	s_mov_b64 s[74:75], 0x80000
	v_writelane_b32 v252, s13, 35
	s_add_u32 s12, s14, 0x2f7c5e00
	s_addc_u32 s13, s15, 0
	v_writelane_b32 v252, s12, 36
	s_mov_b64 s[72:73], 0x9080c00
	s_mov_b64 s[76:77], 0x21200200
	v_writelane_b32 v252, s13, 37
	s_add_u32 s12, s14, 0x2f7c5f00
	s_addc_u32 s13, s15, 0
	v_writelane_b32 v252, s12, 38
	s_cmp_eq_u32 s2, 15
	s_nop 0
	v_writelane_b32 v252, s13, 39
	s_cselect_b64 s[12:13], -1, 0
	v_writelane_b32 v252, s12, 40
	s_cmp_eq_u32 s2, 14
	s_nop 0
	v_writelane_b32 v252, s13, 41
	s_cselect_b64 s[12:13], -1, 0
	v_writelane_b32 v252, s12, 42
	s_cmp_eq_u32 s2, 13
	s_nop 0
	v_writelane_b32 v252, s13, 43
	s_cselect_b64 s[12:13], -1, 0
	v_writelane_b32 v252, s12, 44
	s_cmp_eq_u32 s2, 12
	s_nop 0
	v_writelane_b32 v252, s13, 45
	s_cselect_b64 s[12:13], -1, 0
	v_writelane_b32 v252, s12, 46
	s_cmp_eq_u32 s2, 11
	s_nop 0
	v_writelane_b32 v252, s13, 47
	s_cselect_b64 s[12:13], -1, 0
	v_writelane_b32 v252, s12, 48
	s_cmp_eq_u32 s2, 10
	s_nop 0
	v_writelane_b32 v252, s13, 49
	s_cselect_b64 s[12:13], -1, 0
	v_writelane_b32 v252, s12, 50
	s_cmp_eq_u32 s2, 9
	s_nop 0
	v_writelane_b32 v252, s13, 51
	s_cselect_b64 s[12:13], -1, 0
	v_writelane_b32 v252, s12, 52
	s_cmp_eq_u32 s2, 8
	s_nop 0
	v_writelane_b32 v252, s13, 53
	s_cselect_b64 s[12:13], -1, 0
	v_writelane_b32 v252, s12, 54
	s_cmp_eq_u32 s2, 7
	s_nop 0
	v_writelane_b32 v252, s13, 55
	s_cselect_b64 s[12:13], -1, 0
	v_writelane_b32 v252, s12, 56
	s_cmp_eq_u32 s2, 6
	s_nop 0
	v_writelane_b32 v252, s13, 57
	s_cselect_b64 s[12:13], -1, 0
	v_writelane_b32 v252, s12, 58
	s_cmp_eq_u32 s2, 5
	s_nop 0
	v_writelane_b32 v252, s13, 59
	s_cselect_b64 s[12:13], -1, 0
	v_writelane_b32 v252, s12, 60
	s_cmp_eq_u32 s2, 4
	s_nop 0
	v_writelane_b32 v252, s13, 61
	s_cselect_b64 s[12:13], -1, 0
	v_writelane_b32 v252, s12, 62
	s_cmp_eq_u32 s2, 3
	s_nop 0
	v_writelane_b32 v252, s13, 63
	s_cselect_b64 s[12:13], -1, 0
	v_writelane_b32 v254, s12, 0
	s_cmp_eq_u32 s2, 2
	s_nop 0
	v_writelane_b32 v254, s13, 1
	s_cselect_b64 s[12:13], -1, 0
	v_writelane_b32 v254, s12, 2
	s_cmp_eq_u32 s2, 1
	s_nop 0
	v_writelane_b32 v254, s13, 3
	s_cselect_b64 s[12:13], -1, 0
	v_writelane_b32 v254, s12, 4
	s_cmp_eq_u32 s2, 0
	s_nop 0
	v_writelane_b32 v254, s13, 5
	s_cselect_b64 s[12:13], -1, 0
	s_lshl_b32 s2, s2, 8
	s_add_u32 s2, s10, s2
	s_addc_u32 s3, s11, 0
	v_writelane_b32 v254, s12, 6
	s_add_u32 s10, s2, 0x1400
	s_addc_u32 s11, s3, 0
	v_writelane_b32 v254, s13, 7
	v_writelane_b32 v254, s10, 8
	s_add_u32 s2, s2, 0x2400
	s_addc_u32 s3, s3, 0
	v_writelane_b32 v254, s11, 9
	v_writelane_b32 v254, s2, 10
	s_nop 1
	v_writelane_b32 v254, s3, 11
	s_add_u32 s2, s14, 0x2f7c8000
	s_addc_u32 s3, s15, 0
	v_writelane_b32 v254, s2, 12
	s_nop 1
	v_writelane_b32 v254, s3, 13
	s_add_u32 s2, s14, 0x2f7c8100
	s_addc_u32 s3, s15, 0
	v_writelane_b32 v254, s2, 14
	s_cmpk_lt_i32 s82, 0x100
	s_nop 0
	v_writelane_b32 v254, s3, 15
	s_cselect_b64 s[2:3], -1, 0
	s_add_u32 s28, s58, 0x9080000
	s_addc_u32 s29, s59, 0
	v_writelane_b32 v254, s2, 16
	s_add_u32 s37, s58, 0x29280000
	s_nop 0
	v_writelane_b32 v254, s3, 17
	s_addc_u32 s3, s59, 0
	s_add_u32 s83, s58, 0x2f400000
	s_addc_u32 s33, s59, 0
	s_add_u32 s2, s58, 0x2f504000
	v_writelane_b32 v254, s2, 18
	s_addc_u32 s2, s59, 0
	s_add_u32 s10, s58, 0x21200000
	v_writelane_b32 v254, s2, 19
	s_addc_u32 s11, s59, 0
	v_writelane_b32 v254, s10, 20
	s_cmp_gt_i32 s82, 11
	s_nop 0
	v_writelane_b32 v254, s11, 21
	s_cselect_b64 s[10:11], -1, 0
	v_writelane_b32 v254, s10, 22
	s_nop 1
	v_writelane_b32 v254, s11, 23
	s_add_i32 s10, s82, -12
	s_add_u32 s34, s58, 0x2d380000
	s_mov_b32 s11, s68
	s_addc_u32 s35, s59, 0
	s_lshl_b64 s[10:11], s[10:11], 9
	v_writelane_b32 v254, s10, 24
	s_nop 1
	v_writelane_b32 v254, s11, 25
	s_lshl_b64 s[10:11], s[78:79], 9
	s_add_u32 s10, s10, 0xffffe800
	s_addc_u32 s11, s11, -1
	s_lshl_b32 s2, s9, 1
	s_add_i32 s6, s9, 4
	s_cmp_lt_i32 s9, 4
	s_cselect_b32 s2, s2, s6
	s_add_i32 s2, s2, s8
	v_writelane_b32 v254, s10, 26
	s_mul_hi_i32 s6, s2, 0x2aaaaaab
	s_nop 0
	v_writelane_b32 v254, s11, 27
	s_lshr_b32 s10, s6, 31
	s_ashr_i32 s6, s6, 4
	s_add_i32 s6, s6, s10
	s_lshl_b32 s12, s6, 3
	s_mul_i32 s10, s6, 0x60
	s_sub_i32 s6, 1, s12
	s_min_u32 s13, s6, 8
	s_sub_i32 s2, s2, s10
	v_cvt_f32_ubyte0_e32 v1, s13
	v_cvt_f32_i32_e32 v0, s2
	v_rcp_iflag_f32_e32 v2, v1
	s_ashr_i32 s6, s2, 30
	s_or_b32 s6, s6, 1
	v_mul_f32_e32 v2, v0, v2
	v_trunc_f32_e32 v2, v2
	v_fma_f32 v0, -v2, v1, v0
	v_cmp_ge_f32_e64 s[10:11], |v0|, v1
	v_cvt_i32_f32_e32 v0, v2
	s_and_b64 s[10:11], s[10:11], exec
	s_cselect_b32 s6, s6, 0
	v_readfirstlane_b32 s10, v0
	s_add_i32 s6, s10, s6
	s_mul_i32 s10, s6, s13
	s_sub_i32 s2, s2, s10
	s_sext_i32_i8 s2, s2
	s_add_i32 s12, s12, s2
	s_add_u32 s2, s58, 0x2f584400
	v_writelane_b32 v254, s2, 28
	s_addc_u32 s2, s59, 0
	s_cmpk_lt_i32 s82, 0x110
	s_cselect_b64 s[10:11], -1, 0
	s_add_u32 s87, s56, 0x10980000
	v_writelane_b32 v254, s2, 29
	s_addc_u32 s2, s57, 0
	v_writelane_b32 v254, s10, 30
	s_add_u32 s18, s14, 0x21200000
	s_addc_u32 s19, s15, 0
	v_writelane_b32 v254, s11, 31
	v_writelane_b32 v254, s2, 32
	s_add_u32 s2, s14, 0xc00000
	v_writelane_b32 v254, s2, 33
	s_addc_u32 s2, s15, 0
	s_cmpk_lt_i32 s82, 0x400
	s_cselect_b64 s[10:11], -1, 0
	v_writelane_b32 v254, s2, 34
	s_and_b64 s[4:5], s[10:11], s[4:5]
	s_lshl_b32 s2, s9, 7
	v_writelane_b32 v254, s4, 35
	s_cmp_gt_i32 s82, 3
	s_nop 0
	v_writelane_b32 v254, s5, 36
	s_cselect_b64 s[4:5], -1, 0
	v_writelane_b32 v254, s4, 37
	s_lshl_b32 s15, s82, 3
	s_nop 0
	v_writelane_b32 v254, s5, 38
	s_lshl_b32 s4, s78, 3
	v_writelane_b32 v254, s4, 39
	s_sub_i32 s4, s4, 32
	v_writelane_b32 v254, s4, 40
	s_sub_i32 s4, s15, 32
	v_writelane_b32 v254, s4, 41
	s_add_u32 s4, s58, 0x1000000
	s_addc_u32 s5, s59, 0
	v_writelane_b32 v254, s4, 42
	s_nop 1
	v_writelane_b32 v254, s5, 43
	s_mul_i32 s4, s8, -7
	s_add_i32 s4, s4, s82
	s_ashr_i32 s5, s4, 31
	s_lshr_b32 s5, s5, 27
	s_add_i32 s5, s4, s5
	s_ashr_i32 s5, s5, 5
	s_lshl_b32 s10, s5, 5
	s_lshl_b32 s11, s5, 3
	s_sub_i32 s10, s4, s10
	s_sub_i32 s4, 1, s11
	s_min_u32 s13, s4, 8
	s_sext_i32_i8 s4, s10
	v_cvt_f32_ubyte0_e32 v1, s13
	v_cvt_f32_i32_e32 v0, s4
	v_rcp_iflag_f32_e32 v2, v1
	s_ashr_i32 s4, s4, 30
	s_or_b32 s14, s4, 1
	v_mul_f32_e32 v2, v0, v2
	v_trunc_f32_e32 v2, v2
	v_fma_f32 v0, -v2, v1, v0
	v_cmp_ge_f32_e64 s[4:5], |v0|, v1
	v_cvt_i32_f32_e32 v0, v2
	s_and_b64 s[4:5], s[4:5], exec
	s_cselect_b32 s4, s14, 0
	v_mov_b32_e32 v1, 0
	v_readfirstlane_b32 s5, v0
	s_add_i32 s4, s5, s4
	s_mul_i32 s5, s4, s13
	s_sub_i32 s5, s10, s5
	s_sext_i32_i8 s5, s5
	s_add_i32 s5, s11, s5
	s_cmp_lt_i32 s82, 32
	s_cselect_b64 s[10:11], -1, 0
	v_writelane_b32 v254, s10, 44
	v_mbcnt_lo_u32_b32 v0, -1, 0
	v_mbcnt_hi_u32_b32 v229, -1, v0
	v_writelane_b32 v254, s11, 45
	s_add_i32 s10, s15, 0x10000
	v_writelane_b32 v254, s10, 46
	s_cmp_lt_i32 s9, 0
	s_movk_i32 s10, 0x181
	s_cselect_b32 s10, s10, 0x180
	s_mul_i32 s10, s9, s10
	s_mulk_i32 s9, 0x81
	s_cselect_b32 s2, s9, s2
	s_add_i32 s10, s10, s8
	s_mul_hi_i32 s9, s10, 0x2aaaaaab
	s_lshr_b32 s11, s9, 31
	s_ashr_i32 s9, s9, 4
	s_add_i32 s9, s9, s11
	s_mul_i32 s11, s9, 0x60
	s_sub_i32 s10, s10, s11
	s_bfe_i32 s11, s10, 0x80000
	s_add_i32 s2, s2, s8
	s_bfe_u32 s11, s11, 0x3000c
	s_ashr_i32 s8, s2, 31
	s_add_i32 s11, s10, s11
	s_lshr_b32 s8, s8, 27
	s_and_b32 s13, s11, 0xf8
	s_add_i32 s8, s2, s8
	s_sub_i32 s10, s10, s13
	s_and_b32 s13, s8, 0xffe0
	s_sub_i32 s2, s2, s13
	s_bfe_i32 s13, s2, 0x80000
	s_bfe_u32 s13, s13, 0x3000c
	s_add_i32 s13, s2, s13
	s_and_b32 s14, s13, 0xf8
	s_lshl_b32 s9, s9, 3
	s_sext_i32_i8 s10, s10
	s_sub_i32 s2, s2, s14
	s_add_i32 s10, s9, s10
	s_ashr_i32 s8, s8, 5
	s_bfe_i32 s9, s13, 0x80000
	s_lshl_b32 s8, s8, 3
	s_sext_i32_i16 s9, s9
	s_sext_i32_i8 s2, s2
	s_add_i32 s20, s8, s2
	s_ashr_i32 s2, s9, 3
	v_writelane_b32 v254, s2, 47
	s_lshr_b32 s2, s9, 3
	s_bfe_i64 s[8:9], s[2:3], 0x100000
	s_bfe_i32 s11, s11, 0x80000
	s_lshl_b64 s[8:9], s[8:9], 19
	s_sext_i32_i16 s11, s11
	v_writelane_b32 v254, s8, 48
	s_ashr_i32 s2, s11, 3
	s_ashr_i32 s21, s20, 31
	v_writelane_b32 v254, s9, 49
	v_writelane_b32 v254, s2, 50
	s_mov_b32 s8, s20
	v_writelane_b32 v254, s8, 51
	s_lshr_b32 s2, s11, 3
	s_nop 0
	v_writelane_b32 v254, s9, 52
	s_lshl_b64 s[8:9], s[20:21], 19
	s_add_u32 s8, s18, s8
	s_addc_u32 s9, s19, s9
	s_add_u32 s20, s8, 0x40000
	v_writelane_b32 v254, s8, 53
	s_addc_u32 s21, s9, 0
	s_ashr_i32 s11, s10, 31
	v_writelane_b32 v254, s9, 54
	v_writelane_b32 v254, s20, 55
	s_bfe_i64 s[8:9], s[2:3], 0x100000
	s_lshl_b64 s[8:9], s[8:9], 19
	v_writelane_b32 v254, s21, 56
	v_writelane_b32 v254, s8, 57
	s_mov_b32 s2, s10
	s_nop 0
	v_writelane_b32 v254, s9, 58
	s_lshl_b64 s[8:9], s[10:11], 19
	v_writelane_b32 v254, s2, 59
	s_add_u32 s8, s16, s8
	s_addc_u32 s9, s17, s9
	v_writelane_b32 v254, s3, 60
	s_add_u32 s10, s8, 0x40000
	v_writelane_b32 v254, s8, 61
	s_addc_u32 s11, s9, 0
	s_nop 0
	v_writelane_b32 v254, s9, 62
	s_bfe_i64 s[8:9], s[6:7], 0x80000
	v_writelane_b32 v254, s10, 63
	s_lshl_b64 s[8:9], s[8:9], 19
	s_nop 0
	v_writelane_b32 v253, s11, 0
	s_add_i32 s10, s12, 0x100
	v_writelane_b32 v253, s8, 1
	s_mov_b32 s2, s10
	s_ashr_i32 s11, s10, 31
	v_writelane_b32 v253, s9, 2
	v_writelane_b32 v253, s2, 3
	s_lshl_b64 s[8:9], s[10:11], 19
	s_add_u32 s8, s16, s8
	v_writelane_b32 v253, s3, 4
	v_writelane_b32 v253, s16, 5
	v_writelane_b32 v253, s17, 6
	s_addc_u32 s9, s17, s9
	s_add_u32 s10, s8, 0x40000
	v_writelane_b32 v253, s8, 7
	s_addc_u32 s11, s9, 0
	s_nop 0
	v_writelane_b32 v253, s9, 8
	v_writelane_b32 v253, s10, 9
	s_bfe_i64 s[8:9], s[4:5], 0x80000
	s_lshl_b64 s[8:9], s[8:9], 19
	v_writelane_b32 v253, s11, 10
	s_add_i32 s10, s5, 0x100
	v_writelane_b32 v253, s8, 11
	s_mov_b32 s2, s10
	s_ashr_i32 s11, s10, 31
	v_writelane_b32 v253, s9, 12
	v_writelane_b32 v253, s2, 13
	s_lshl_b64 s[8:9], s[10:11], 19
	s_add_u32 s8, s18, s8
	v_writelane_b32 v253, s3, 14
	s_load_dword s2, s[0:1], 0xb8
	v_writelane_b32 v253, s18, 15
	v_writelane_b32 v253, s19, 16
	s_addc_u32 s9, s19, s9
	s_barrier
	s_waitcnt lgkmcnt(0)
	s_mul_i32 s2, s7, s2
	v_writelane_b32 v253, s2, 17
	s_sext_i32_i8 s2, s6
	v_writelane_b32 v253, s2, 18
	s_sext_i32_i8 s2, s4
	v_writelane_b32 v253, s2, 19
	s_add_u32 s4, s8, 0x40000
	v_writelane_b32 v253, s8, 20
	s_addc_u32 s5, s9, 0
	s_lshl_b32 s2, s82, 9
	v_writelane_b32 v253, s9, 21
	v_writelane_b32 v253, s4, 22
	s_nop 1
	v_writelane_b32 v253, s5, 23
	s_add_i32 s4, s2, 0x2800
	v_writelane_b32 v253, s4, 24
	s_addk_i32 s2, 0x800
	v_writelane_b32 v253, s2, 25
	s_lshl_b32 s2, s78, 9
	s_add_i32 s4, s2, 0x2800
	v_writelane_b32 v253, s4, 26
	s_addk_i32 s2, 0x800
	v_writelane_b32 v253, s2, 27
	s_lshl_b32 s2, s82, 6
	s_add_i32 s2, s2, 0xc000
	v_writelane_b32 v253, s2, 28
	s_lshl_b32 s2, s78, 2
	v_writelane_b32 v253, s2, 29
	s_lshl_b32 s2, s78, 6
	v_writelane_b32 v253, s2, 30
	s_lshl_b32 s2, s78, 8
	v_writelane_b32 v253, s2, 31
	s_lshl_b32 s2, s78, 7
	v_writelane_b32 v253, s2, 32
	s_lshl_b32 s2, s82, 2
	v_writelane_b32 v253, s2, 33
	s_lshl_b32 s2, s82, 8
	v_writelane_b32 v253, s2, 34
	s_lshl_b32 s2, s78, 4
	v_writelane_b32 v253, s2, 35
	s_load_dwordx4 s[4:7], s[0:1], 0x58
	v_writelane_b32 v253, s15, 36
	s_add_i32 s2, s15, 0x10100
	v_writelane_b32 v253, s2, 37
	s_add_i32 s2, 0, 0x25ff0
	v_writelane_b32 v253, s2, 38
	s_add_i32 s2, 0, 0x25ff4
	v_writelane_b32 v253, s2, 39
	s_waitcnt lgkmcnt(0)
	v_writelane_b32 v253, s4, 40
	s_add_i32 s2, 0, 0x1b000
	s_nop 0
	v_writelane_b32 v253, s5, 41
	v_writelane_b32 v253, s6, 42
	v_writelane_b32 v253, s7, 43
	v_writelane_b32 v253, s90, 44
	s_nop 1
	v_writelane_b32 v253, s91, 45
	v_writelane_b32 v253, s81, 46
	v_writelane_b32 v253, s92, 47
	s_nop 1
	v_writelane_b32 v253, s93, 48
	v_writelane_b32 v253, s94, 49
	s_nop 1
	v_writelane_b32 v253, s95, 50
	v_writelane_b32 v253, s96, 51
	s_nop 1
	v_writelane_b32 v253, s97, 52
	v_writelane_b32 v253, s88, 53
	s_nop 1
	v_writelane_b32 v253, s89, 54
	v_writelane_b32 v253, s40, 55
	s_nop 1
	v_writelane_b32 v253, s41, 56
	v_writelane_b32 v253, s83, 57
	v_writelane_b32 v253, s87, 58
	s_mov_b32 s101, 0x51ed
	s_branch .Ltr1
.LBB0_47:
	s_cmp_eq_u32 s101, 0x51ed
	s_cbranch_scc0 .Lnormal47
	s_mov_b32 s101, 0
	s_branch .LBB0_48

.Ltr1:
	s_branch .Ltr2

.LBB0_1511:
	s_or_b64 exec, exec, s[0:1]
	v_readlane_b32 s0, v254, 44
	v_readlane_b32 s1, v254, 45
	s_andn2_b64 vcc, exec, s[0:1]
	s_waitcnt lgkmcnt(0)
	s_barrier
	s_cmp_eq_u32 s101, 0x51ed
	s_cbranch_scc1 .Lpro_ret
	s_cbranch_vccz .LBB0_1512
.Lpro_ret:
	s_getpc_b64 s[98:99]
